# mLSTM chain: counted vmcnt waits re-derived so the 7-chunk prefetch stays in flight (on top of barrier invalidate move)
# baseline (speedup 1.0000x reference)
.LBB0_1214:
	s_waitcnt lgkmcnt(0)
	s_barrier
	s_add_u32 s12, s12, 32
	s_addc_u32 s13, s13, 0
	s_add_i32 s29, s29, 8
	s_add_i32 s28, s28, 64
	v_lshl_add_u64 v[102:103], v[102:103], 0, s[14:15]
	v_lshl_add_u64 v[104:105], v[104:105], 0, s[14:15]
	v_lshl_add_u64 v[106:107], v[106:107], 0, s[20:21]
	s_cmp_gt_u32 s29, 55
	v_lshl_add_u64 v[108:109], v[108:109], 0, s[20:21]
	s_cbranch_scc1 .LBB0_1077
	s_cmp_lg_u32 s29, 48
	s_cbranch_scc1 .LBB0_1215
	s_waitcnt vmcnt(0)

.LBB0_1217:
	s_or_b64 exec, exec, s[22:23]
	s_and_saveexec_b64 s[22:23], s[8:9]
	s_cbranch_execz .LBB0_1219
	s_waitcnt vmcnt(19)
	ds_write_b128 v131, v[22:25] offset:4608
.LBB0_1219:
	s_or_b64 exec, exec, s[22:23]
	v_mov_b32_e32 v110, s28
	ds_read_b128 v[134:137], v133
	ds_read_b64 v[110:111], v110
	ds_read_b128 v[138:141], v133 offset:64
	ds_read_b128 v[146:149], v133 offset:2304
	s_waitcnt vmcnt(16) lgkmcnt(3)
	v_mfma_f32_16x16x32_bf16 v[142:145], v[2:5], v[134:137], 0
	s_waitcnt lgkmcnt(2)
	v_add_f32_e32 v110, v115, v110
	v_max_f32_e32 v111, v111, v111
	v_max_f32_e32 v134, v110, v111
	v_sub_f32_e32 v110, v110, v134
	v_mul_f32_e32 v110, 0x3fb8aa3b, v110
	v_exp_f32_e32 v110, v110
	v_mul_f32_e32 v111, 0xbfb8aa3b, v134
	s_waitcnt vmcnt(15) lgkmcnt(1)
	v_mfma_f32_16x16x32_bf16 v[136:139], v[6:9], v[138:141], v[142:145]
	v_mul_f32_e64 v114, v126, v110
	v_mul_f32_e64 v115, v127, v110
	v_pk_mul_f32 v[124:125], v[124:125], v[110:111] op_sel_hi:[1,0]
	ds_read_b128 v[140:143], v133 offset:2368
	s_waitcnt lgkmcnt(1)
	v_mfma_f32_16x16x32_bf16 v[144:147], v[2:5], v[146:149], 0
	v_exp_f32_e32 v148, v111
	s_nop 0
	v_pk_fma_f32 v[124:125], v[138:139], v[148:149], v[124:125] op_sel_hi:[1,0,1]
	v_pk_fma_f32 v[128:129], v[136:137], v[148:149], v[114:115] op_sel_hi:[1,0,1]
	v_mfma_f32_16x16x32_bf16 v[136:139], v[2:5], v[86:89], 0
	s_waitcnt lgkmcnt(0)
	v_mfma_f32_16x16x32_bf16 v[140:143], v[6:9], v[140:143], v[144:147]
	v_mfma_f32_16x16x32_bf16 v[136:139], v[6:9], v[86:89], v[136:139]
	s_nop 6
	v_mul_f32_e64 v114, v148, v142
	v_mul_f32_e64 v115, v148, v143
	v_pk_mul_f32 v[126:127], v[148:149], v[140:141] op_sel_hi:[0,1]
	v_pk_fma_f32 v[114:115], v[122:123], v[110:111], v[114:115] op_sel_hi:[1,0,1]
	v_pk_fma_f32 v[118:119], v[118:119], v[110:111], v[126:127] op_sel_hi:[1,0,1]
	v_pk_mul_f32 v[122:123], v[110:111], v[120:121] op_sel_hi:[0,1]
	v_pk_mul_f32 v[110:111], v[110:111], v[116:117] op_sel_hi:[0,1]
	v_pk_fma_f32 v[120:121], v[148:149], v[138:139], v[110:111] op_sel_hi:[0,1,1]
	v_lshl_add_u64 v[110:111], s[16:17], 0, v[104:105]
	v_pk_fma_f32 v[126:127], v[148:149], v[136:137], v[122:123] op_sel_hi:[0,1,1]
	v_cvt_pk_bf16_f32 v136, v128, v129
	v_cvt_pk_bf16_f32 v138, v118, v119
	v_cvt_pk_bf16_f32 v137, v124, v125
	v_cvt_pk_bf16_f32 v139, v114, v115
	v_add_co_u32_e32 v116, vcc, 0x9008000, v110
	v_permlane16_swap_b32_e32 v136, v138
	v_permlane16_swap_b32_e32 v137, v139
	v_addc_co_u32_e32 v117, vcc, 0, v111, vcc
	global_store_dwordx4 v[116:117], v[136:139], off offset:256
	s_and_saveexec_b64 s[22:23], s[10:11]
	s_cbranch_execz .LBB0_1221
	v_lshl_add_u64 v[122:123], s[16:17], 0, v[102:103]
	v_add_co_u32_e32 v122, vcc, 0x9010000, v122
	v_cvt_pk_bf16_f32 v116, v126, v127
	v_cvt_pk_bf16_f32 v117, v120, v121
	v_addc_co_u32_e32 v123, vcc, 0, v123, vcc
	global_store_dwordx2 v[122:123], v[116:117], off offset:256

.LBB0_1227:
	s_and_saveexec_b64 s[22:23], s[8:9]
	s_cbranch_execz .LBB0_1229
	s_waitcnt vmcnt(20)
	ds_write_b128 v131, v[34:37] offset:9216
.LBB0_1229:
	s_or_b64 exec, exec, s[22:23]
	v_mov_b32_e32 v116, s28
	ds_read_b128 v[136:139], v133 offset:4608
	ds_read_b64 v[116:117], v116 offset:8
	ds_read_b128 v[140:143], v133 offset:4672
	ds_read_b128 v[144:147], v133 offset:6912
	s_waitcnt vmcnt(17) lgkmcnt(3)
	v_mfma_f32_16x16x32_bf16 v[136:139], v[14:17], v[136:139], 0
	s_waitcnt lgkmcnt(2)
	v_add_f32_e32 v116, v134, v116
	v_max_f32_e32 v117, v117, v117
	v_max_f32_e32 v134, v116, v117
	v_sub_f32_e32 v116, v116, v134
	v_mul_f32_e32 v116, 0x3fb8aa3b, v116
	v_exp_f32_e32 v148, v116
	v_mul_f32_e32 v116, 0xbfb8aa3b, v134
	s_waitcnt vmcnt(16) lgkmcnt(1)
	v_mfma_f32_16x16x32_bf16 v[136:139], v[18:21], v[140:143], v[136:139]
	v_exp_f32_e32 v150, v116
	ds_read_b128 v[140:143], v133 offset:6976
	v_pk_mul_f32 v[116:117], v[128:129], v[148:149] op_sel_hi:[1,0]
	s_waitcnt lgkmcnt(1)
	v_mfma_f32_16x16x32_bf16 v[144:147], v[14:17], v[144:147], 0
	v_mul_f32_e64 v122, v124, v148
	v_mul_f32_e64 v123, v125, v148
	s_nop 0
	v_pk_fma_f32 v[128:129], v[136:137], v[150:151], v[116:117] op_sel_hi:[1,0,1]
	v_pk_fma_f32 v[124:125], v[138:139], v[150:151], v[122:123] op_sel_hi:[1,0,1]
	v_mfma_f32_16x16x32_bf16 v[136:139], v[14:17], v[86:89], 0
	s_waitcnt lgkmcnt(0)
	v_mfma_f32_16x16x32_bf16 v[140:143], v[18:21], v[140:143], v[144:147]
	v_mfma_f32_16x16x32_bf16 v[136:139], v[18:21], v[86:89], v[136:139]
	s_nop 6
	v_mul_f32_e64 v116, v150, v142
	v_mul_f32_e64 v117, v150, v143
	v_pk_mul_f32 v[122:123], v[150:151], v[140:141] op_sel_hi:[0,1]
	v_pk_fma_f32 v[116:117], v[114:115], v[148:149], v[116:117] op_sel_hi:[1,0,1]
	v_pk_fma_f32 v[122:123], v[118:119], v[148:149], v[122:123] op_sel_hi:[1,0,1]
	v_pk_mul_f32 v[114:115], v[150:151], v[138:139] op_sel_hi:[0,1]
	v_pk_mul_f32 v[118:119], v[150:151], v[136:137] op_sel_hi:[0,1]
	v_pk_fma_f32 v[114:115], v[120:121], v[148:149], v[114:115] op_sel_hi:[1,0,1]
	v_cvt_pk_bf16_f32 v136, v128, v129
	v_cvt_pk_bf16_f32 v138, v122, v123
	v_cvt_pk_bf16_f32 v137, v124, v125
	v_cvt_pk_bf16_f32 v139, v116, v117
	v_add_co_u32_e32 v120, vcc, 0x9010000, v110
	v_pk_fma_f32 v[118:119], v[126:127], v[148:149], v[118:119] op_sel_hi:[1,0,1]
	v_permlane16_swap_b32_e32 v136, v138
	v_permlane16_swap_b32_e32 v137, v139
	v_addc_co_u32_e32 v121, vcc, 0, v111, vcc
	global_store_dwordx4 v[120:121], v[136:139], off offset:512
	s_and_saveexec_b64 s[22:23], s[10:11]
	s_cbranch_execz .LBB0_1231
	v_lshl_add_u64 v[126:127], s[16:17], 0, v[102:103]
	v_add_co_u32_e32 v126, vcc, 0x9018000, v126
	v_cvt_pk_bf16_f32 v120, v118, v119
	v_cvt_pk_bf16_f32 v121, v114, v115
	v_addc_co_u32_e32 v127, vcc, 0, v127, vcc
	global_store_dwordx2 v[126:127], v[120:121], off offset:512

.LBB0_1237:
	s_and_saveexec_b64 s[22:23], s[8:9]
	s_cbranch_execz .LBB0_1239
	s_waitcnt vmcnt(21)
	ds_write_b128 v131, v[46:49] offset:13824
.LBB0_1239:
	s_or_b64 exec, exec, s[22:23]
	v_mov_b32_e32 v120, s28
	ds_read_b128 v[136:139], v133 offset:9216
	ds_read_b64 v[120:121], v120 offset:16
	ds_read_b128 v[140:143], v133 offset:9280
	ds_read_b128 v[144:147], v133 offset:11520
	s_waitcnt vmcnt(18) lgkmcnt(3)
	v_mfma_f32_16x16x32_bf16 v[136:139], v[26:29], v[136:139], 0
	s_waitcnt lgkmcnt(2)
	v_add_f32_e32 v120, v134, v120
	v_max_f32_e32 v121, v121, v121
	v_max_f32_e32 v134, v120, v121
	v_sub_f32_e32 v120, v120, v134
	v_mul_f32_e32 v120, 0x3fb8aa3b, v120
	v_exp_f32_e32 v148, v120
	v_mul_f32_e32 v120, 0xbfb8aa3b, v134
	s_waitcnt vmcnt(17) lgkmcnt(1)
	v_mfma_f32_16x16x32_bf16 v[136:139], v[30:33], v[140:143], v[136:139]
	v_exp_f32_e32 v150, v120
	ds_read_b128 v[140:143], v133 offset:11584
	v_pk_mul_f32 v[120:121], v[128:129], v[148:149] op_sel_hi:[1,0]
	s_waitcnt lgkmcnt(1)
	v_mfma_f32_16x16x32_bf16 v[144:147], v[26:29], v[144:147], 0
	v_mul_f32_e64 v124, v124, v148
	v_mul_f32_e64 v125, v125, v148
	s_nop 0
	v_pk_fma_f32 v[126:127], v[136:137], v[150:151], v[120:121] op_sel_hi:[1,0,1]
	v_pk_fma_f32 v[124:125], v[138:139], v[150:151], v[124:125] op_sel_hi:[1,0,1]
	v_mfma_f32_16x16x32_bf16 v[136:139], v[26:29], v[86:89], 0
	s_waitcnt lgkmcnt(0)
	v_mfma_f32_16x16x32_bf16 v[140:143], v[30:33], v[140:143], v[144:147]
	v_mfma_f32_16x16x32_bf16 v[136:139], v[30:33], v[86:89], v[136:139]
	s_nop 6
	v_mul_f32_e64 v120, v150, v142
	v_mul_f32_e64 v121, v150, v143
	v_pk_mul_f32 v[128:129], v[150:151], v[140:141] op_sel_hi:[0,1]
	v_pk_fma_f32 v[116:117], v[116:117], v[148:149], v[120:121] op_sel_hi:[1,0,1]
	v_pk_fma_f32 v[120:121], v[122:123], v[148:149], v[128:129] op_sel_hi:[1,0,1]
	v_pk_mul_f32 v[122:123], v[150:151], v[138:139] op_sel_hi:[0,1]
	v_pk_mul_f32 v[128:129], v[150:151], v[136:137] op_sel_hi:[0,1]
	v_pk_fma_f32 v[114:115], v[114:115], v[148:149], v[122:123] op_sel_hi:[1,0,1]
	v_cvt_pk_bf16_f32 v136, v126, v127
	v_cvt_pk_bf16_f32 v138, v120, v121
	v_cvt_pk_bf16_f32 v137, v124, v125
	v_cvt_pk_bf16_f32 v139, v116, v117
	v_add_co_u32_e32 v122, vcc, 0x9018000, v110
	v_pk_fma_f32 v[118:119], v[118:119], v[148:149], v[128:129] op_sel_hi:[1,0,1]
	v_permlane16_swap_b32_e32 v136, v138
	v_permlane16_swap_b32_e32 v137, v139
	v_addc_co_u32_e32 v123, vcc, 0, v111, vcc
	global_store_dwordx4 v[122:123], v[136:139], off offset:768
	s_and_saveexec_b64 s[22:23], s[10:11]
	s_cbranch_execz .LBB0_1241
	v_lshl_add_u64 v[128:129], s[16:17], 0, v[102:103]
	v_add_co_u32_e32 v128, vcc, 0x9020000, v128
	v_cvt_pk_bf16_f32 v122, v118, v119
	v_cvt_pk_bf16_f32 v123, v114, v115
	v_addc_co_u32_e32 v129, vcc, 0, v129, vcc
	global_store_dwordx2 v[128:129], v[122:123], off offset:768

.LBB0_1247:
	s_and_saveexec_b64 s[22:23], s[8:9]
	s_cbranch_execz .LBB0_1249
	s_waitcnt vmcnt(22)
	ds_write_b128 v131, v[58:61] offset:18432
.LBB0_1249:
	s_or_b64 exec, exec, s[22:23]
	v_mov_b32_e32 v122, s28
	ds_read_b128 v[136:139], v133 offset:13824
	ds_read_b64 v[122:123], v122 offset:24
	ds_read_b128 v[140:143], v133 offset:13888
	ds_read_b128 v[144:147], v133 offset:16128
	s_waitcnt vmcnt(19) lgkmcnt(3)
	v_mfma_f32_16x16x32_bf16 v[136:139], v[38:41], v[136:139], 0
	s_waitcnt lgkmcnt(2)
	v_add_f32_e32 v122, v134, v122
	v_max_f32_e32 v123, v123, v123
	v_max_f32_e32 v128, v122, v123
	v_sub_f32_e32 v122, v122, v128
	v_mul_f32_e32 v122, 0x3fb8aa3b, v122
	v_exp_f32_e32 v148, v122
	v_mul_f32_e32 v122, 0xbfb8aa3b, v128
	s_waitcnt vmcnt(18) lgkmcnt(1)
	v_mfma_f32_16x16x32_bf16 v[134:137], v[42:45], v[140:143], v[136:139]
	v_mul_f32_e64 v126, v126, v148
	v_mul_f32_e64 v127, v127, v148
	s_nop 0
	ds_read_b128 v[138:141], v133 offset:16192
	s_waitcnt lgkmcnt(1)
	v_mfma_f32_16x16x32_bf16 v[142:145], v[38:41], v[144:147], 0
	v_exp_f32_e32 v146, v122
	v_pk_mul_f32 v[122:123], v[124:125], v[148:149] op_sel_hi:[1,0]
	v_pk_fma_f32 v[124:125], v[134:135], v[146:147], v[126:127] op_sel_hi:[1,0,1]
	v_pk_fma_f32 v[122:123], v[136:137], v[146:147], v[122:123] op_sel_hi:[1,0,1]
	v_mfma_f32_16x16x32_bf16 v[134:137], v[38:41], v[86:89], 0
	s_waitcnt lgkmcnt(0)
	v_mfma_f32_16x16x32_bf16 v[138:141], v[42:45], v[138:141], v[142:145]
	v_mfma_f32_16x16x32_bf16 v[134:137], v[42:45], v[86:89], v[134:137]
	s_nop 6
	v_mul_f32_e64 v126, v146, v140
	v_mul_f32_e64 v127, v146, v141
	v_pk_mul_f32 v[138:139], v[146:147], v[138:139] op_sel_hi:[0,1]
	v_pk_fma_f32 v[116:117], v[116:117], v[148:149], v[126:127] op_sel_hi:[1,0,1]
	v_pk_fma_f32 v[120:121], v[120:121], v[148:149], v[138:139] op_sel_hi:[1,0,1]
	v_pk_mul_f32 v[126:127], v[146:147], v[136:137] op_sel_hi:[0,1]
	v_pk_mul_f32 v[134:135], v[146:147], v[134:135] op_sel_hi:[0,1]
	v_pk_fma_f32 v[114:115], v[114:115], v[148:149], v[126:127] op_sel_hi:[1,0,1]
	v_pk_fma_f32 v[118:119], v[118:119], v[148:149], v[134:135] op_sel_hi:[1,0,1]
	v_cvt_pk_bf16_f32 v134, v124, v125
	v_cvt_pk_bf16_f32 v136, v120, v121
	v_cvt_pk_bf16_f32 v135, v122, v123
	v_cvt_pk_bf16_f32 v137, v116, v117
	v_add_co_u32_e32 v126, vcc, 0x9020000, v110
	v_permlane16_swap_b32_e32 v134, v136
	v_permlane16_swap_b32_e32 v135, v137
	v_addc_co_u32_e32 v127, vcc, 0, v111, vcc
	global_store_dwordx4 v[126:127], v[134:137], off offset:1024
	s_and_saveexec_b64 s[22:23], s[10:11]
	s_cbranch_execz .LBB0_1251
	v_lshl_add_u64 v[134:135], s[16:17], 0, v[102:103]
	v_add_co_u32_e32 v134, vcc, 0x9028000, v134
	v_cvt_pk_bf16_f32 v126, v118, v119
	v_cvt_pk_bf16_f32 v127, v114, v115
	v_addc_co_u32_e32 v135, vcc, 0, v135, vcc
	global_store_dwordx2 v[134:135], v[126:127], off offset:1024

.LBB0_1257:
	s_and_saveexec_b64 s[22:23], s[8:9]
	s_cbranch_execz .LBB0_1259
	s_waitcnt vmcnt(23)
	ds_write_b128 v131, v[70:73] offset:23040
.LBB0_1259:
	s_or_b64 exec, exec, s[22:23]
	v_mov_b32_e32 v126, s28
	ds_read_b128 v[134:137], v133 offset:18432
	ds_read_b64 v[126:127], v126 offset:32
	ds_read_b128 v[138:141], v133 offset:18496
	ds_read_b128 v[142:145], v133 offset:20736
	s_waitcnt vmcnt(20) lgkmcnt(3)
	v_mfma_f32_16x16x32_bf16 v[134:137], v[50:53], v[134:137], 0
	s_waitcnt lgkmcnt(2)
	v_add_f32_e32 v128, v128, v126
	v_max_f32_e32 v126, v127, v127
	v_max_f32_e32 v126, v128, v126
	v_sub_f32_e32 v127, v128, v126
	v_mul_f32_e32 v127, 0x3fb8aa3b, v127
	v_exp_f32_e32 v128, v127
	v_mul_f32_e32 v127, 0xbfb8aa3b, v126
	s_waitcnt vmcnt(19) lgkmcnt(1)
	v_mfma_f32_16x16x32_bf16 v[134:137], v[54:57], v[138:141], v[134:137]
	v_exp_f32_e32 v146, v127
	ds_read_b128 v[138:141], v133 offset:20800
	v_pk_mul_f32 v[124:125], v[124:125], v[128:129] op_sel_hi:[1,0]
	s_waitcnt lgkmcnt(1)
	v_mfma_f32_16x16x32_bf16 v[142:145], v[50:53], v[142:145], 0
	v_mul_f32_e64 v122, v122, v128
	v_mul_f32_e64 v123, v123, v128
	s_nop 0
	v_pk_fma_f32 v[124:125], v[134:135], v[146:147], v[124:125] op_sel_hi:[1,0,1]
	v_pk_fma_f32 v[122:123], v[136:137], v[146:147], v[122:123] op_sel_hi:[1,0,1]
	v_mfma_f32_16x16x32_bf16 v[134:137], v[50:53], v[86:89], 0
	s_waitcnt lgkmcnt(0)
	v_mfma_f32_16x16x32_bf16 v[138:141], v[54:57], v[138:141], v[142:145]
	v_mfma_f32_16x16x32_bf16 v[134:137], v[54:57], v[86:89], v[134:137]
	s_nop 6
	v_mul_f32_e64 v140, v146, v140
	v_mul_f32_e64 v141, v146, v141
	v_pk_mul_f32 v[138:139], v[146:147], v[138:139] op_sel_hi:[0,1]
	v_pk_fma_f32 v[116:117], v[116:117], v[128:129], v[140:141] op_sel_hi:[1,0,1]
	v_pk_fma_f32 v[120:121], v[120:121], v[128:129], v[138:139] op_sel_hi:[1,0,1]
	v_pk_mul_f32 v[136:137], v[146:147], v[136:137] op_sel_hi:[0,1]
	v_pk_mul_f32 v[134:135], v[146:147], v[134:135] op_sel_hi:[0,1]
	v_pk_fma_f32 v[114:115], v[114:115], v[128:129], v[136:137] op_sel_hi:[1,0,1]
	v_pk_fma_f32 v[118:119], v[118:119], v[128:129], v[134:135] op_sel_hi:[1,0,1]
	v_cvt_pk_bf16_f32 v134, v124, v125
	v_cvt_pk_bf16_f32 v136, v120, v121
	v_cvt_pk_bf16_f32 v135, v122, v123
	v_cvt_pk_bf16_f32 v137, v116, v117
	v_add_co_u32_e32 v128, vcc, 0x9028000, v110
	v_permlane16_swap_b32_e32 v134, v136
	v_permlane16_swap_b32_e32 v135, v137
	v_addc_co_u32_e32 v129, vcc, 0, v111, vcc
	global_store_dwordx4 v[128:129], v[134:137], off offset:1280
	s_and_saveexec_b64 s[22:23], s[10:11]
	s_cbranch_execz .LBB0_1261
	v_lshl_add_u64 v[134:135], s[16:17], 0, v[102:103]
	v_add_co_u32_e32 v134, vcc, 0x9030000, v134
	v_cvt_pk_bf16_f32 v128, v118, v119
	v_cvt_pk_bf16_f32 v129, v114, v115
	v_addc_co_u32_e32 v135, vcc, 0, v135, vcc
	global_store_dwordx2 v[134:135], v[128:129], off offset:1280

.LBB0_1267:
	s_and_saveexec_b64 s[22:23], s[8:9]
	s_cbranch_execz .LBB0_1269
	s_waitcnt vmcnt(24)
	ds_write_b128 v131, v[82:85] offset:27648
.LBB0_1269:
	s_or_b64 exec, exec, s[22:23]
	v_mov_b32_e32 v127, s28
	ds_read_b128 v[134:137], v133 offset:23040
	ds_read_b64 v[128:129], v127 offset:40
	ds_read_b128 v[138:141], v133 offset:23104
	ds_read_b128 v[142:145], v133 offset:25344
	s_waitcnt vmcnt(21) lgkmcnt(3)
	v_mfma_f32_16x16x32_bf16 v[134:137], v[62:65], v[134:137], 0
	s_waitcnt lgkmcnt(2)
	v_add_f32_e32 v126, v126, v128
	v_max_f32_e32 v127, v129, v129
	v_max_f32_e32 v128, v126, v127
	v_sub_f32_e32 v126, v126, v128
	v_mul_f32_e32 v126, 0x3fb8aa3b, v126
	v_exp_f32_e32 v146, v126
	v_mul_f32_e32 v126, 0xbfb8aa3b, v128
	s_waitcnt vmcnt(20) lgkmcnt(1)
	v_mfma_f32_16x16x32_bf16 v[134:137], v[66:69], v[138:141], v[134:137]
	v_exp_f32_e32 v148, v126
	ds_read_b128 v[138:141], v133 offset:25408
	v_pk_mul_f32 v[124:125], v[124:125], v[146:147] op_sel_hi:[1,0]
	s_waitcnt lgkmcnt(1)
	v_mfma_f32_16x16x32_bf16 v[142:145], v[62:65], v[142:145], 0
	v_mul_f32_e64 v122, v122, v146
	v_mul_f32_e64 v123, v123, v146
	s_nop 0
	v_pk_fma_f32 v[126:127], v[134:135], v[148:149], v[124:125] op_sel_hi:[1,0,1]
	v_pk_fma_f32 v[122:123], v[136:137], v[148:149], v[122:123] op_sel_hi:[1,0,1]
	v_mfma_f32_16x16x32_bf16 v[134:137], v[62:65], v[86:89], 0
	s_waitcnt lgkmcnt(0)
	v_mfma_f32_16x16x32_bf16 v[138:141], v[66:69], v[138:141], v[142:145]
	v_mfma_f32_16x16x32_bf16 v[134:137], v[66:69], v[86:89], v[134:137]
	s_nop 6
	v_mul_f32_e64 v124, v148, v140
	v_mul_f32_e64 v125, v148, v141
	v_pk_mul_f32 v[138:139], v[148:149], v[138:139] op_sel_hi:[0,1]
	v_pk_fma_f32 v[116:117], v[116:117], v[146:147], v[124:125] op_sel_hi:[1,0,1]
	v_pk_fma_f32 v[124:125], v[120:121], v[146:147], v[138:139] op_sel_hi:[1,0,1]
	v_pk_mul_f32 v[120:121], v[148:149], v[136:137] op_sel_hi:[0,1]
	v_pk_mul_f32 v[134:135], v[148:149], v[134:135] op_sel_hi:[0,1]
	v_pk_fma_f32 v[114:115], v[114:115], v[146:147], v[120:121] op_sel_hi:[1,0,1]
	v_pk_fma_f32 v[120:121], v[118:119], v[146:147], v[134:135] op_sel_hi:[1,0,1]
	v_cvt_pk_bf16_f32 v134, v126, v127
	v_cvt_pk_bf16_f32 v136, v124, v125
	v_cvt_pk_bf16_f32 v135, v122, v123
	v_cvt_pk_bf16_f32 v137, v116, v117
	v_add_co_u32_e32 v118, vcc, 0x9030000, v110
	v_permlane16_swap_b32_e32 v134, v136
	v_permlane16_swap_b32_e32 v135, v137
	v_addc_co_u32_e32 v119, vcc, 0, v111, vcc
	global_store_dwordx4 v[118:119], v[134:137], off offset:1536
	s_and_saveexec_b64 s[22:23], s[10:11]
	s_cbranch_execz .LBB0_1271
	v_lshl_add_u64 v[134:135], s[16:17], 0, v[102:103]
	v_add_co_u32_e32 v134, vcc, 0x9038000, v134
	v_cvt_pk_bf16_f32 v118, v120, v121
	v_cvt_pk_bf16_f32 v119, v114, v115
	v_addc_co_u32_e32 v135, vcc, 0, v135, vcc
	global_store_dwordx2 v[134:135], v[118:119], off offset:1536

.LBB0_1277:
	s_and_saveexec_b64 s[22:23], s[8:9]
	s_cbranch_execz .LBB0_1279
	s_cmp_lg_u32 s29, 48
	s_cbranch_scc1 .Lch_rlx_18
	s_waitcnt vmcnt(6)
.Lch_rlx_18:
	s_waitcnt vmcnt(24)
	ds_write_b128 v131, v[90:93] offset:32256
.LBB0_1279:
	s_or_b64 exec, exec, s[22:23]
	v_mov_b32_e32 v118, s28
	ds_read_b128 v[134:137], v133 offset:27648
	ds_read_b64 v[118:119], v118 offset:48
	ds_read_b128 v[138:141], v133 offset:27712
	ds_read_b128 v[146:149], v133 offset:29952
	s_waitcnt vmcnt(22) lgkmcnt(3)
	v_mfma_f32_16x16x32_bf16 v[142:145], v[74:77], v[134:137], 0
	s_waitcnt lgkmcnt(2)
	v_add_f32_e32 v118, v128, v118
	v_max_f32_e32 v119, v119, v119
	v_max_f32_e32 v134, v118, v119
	v_sub_f32_e32 v118, v118, v134
	v_mul_f32_e32 v118, 0x3fb8aa3b, v118
	v_exp_f32_e32 v150, v118
	v_mul_f32_e32 v118, 0xbfb8aa3b, v134
	s_waitcnt vmcnt(21) lgkmcnt(1)
	v_mfma_f32_16x16x32_bf16 v[136:139], v[78:81], v[138:141], v[142:145]
	v_mul_f32_e64 v122, v122, v150
	v_mul_f32_e64 v123, v123, v150
	s_nop 0
	ds_read_b128 v[140:143], v133 offset:30016
	s_waitcnt lgkmcnt(1)
	v_mfma_f32_16x16x32_bf16 v[144:147], v[74:77], v[146:149], 0
	v_exp_f32_e32 v148, v118
	v_pk_mul_f32 v[118:119], v[126:127], v[150:151] op_sel_hi:[1,0]
	v_pk_fma_f32 v[122:123], v[138:139], v[148:149], v[122:123] op_sel_hi:[1,0,1]
	v_pk_fma_f32 v[126:127], v[136:137], v[148:149], v[118:119] op_sel_hi:[1,0,1]
	v_mfma_f32_16x16x32_bf16 v[136:139], v[74:77], v[86:89], 0
	s_waitcnt lgkmcnt(0)
	v_mfma_f32_16x16x32_bf16 v[140:143], v[78:81], v[140:143], v[144:147]
	v_mfma_f32_16x16x32_bf16 v[136:139], v[78:81], v[86:89], v[136:139]
	s_nop 6
	v_mul_f32_e64 v118, v148, v142
	v_mul_f32_e64 v119, v148, v143
	v_pk_mul_f32 v[128:129], v[148:149], v[140:141] op_sel_hi:[0,1]
	v_pk_fma_f32 v[118:119], v[116:117], v[150:151], v[118:119] op_sel_hi:[1,0,1]
	v_pk_fma_f32 v[128:129], v[124:125], v[150:151], v[128:129] op_sel_hi:[1,0,1]
	v_pk_mul_f32 v[116:117], v[148:149], v[138:139] op_sel_hi:[0,1]
	v_pk_mul_f32 v[124:125], v[148:149], v[136:137] op_sel_hi:[0,1]
	v_pk_fma_f32 v[116:117], v[114:115], v[150:151], v[116:117] op_sel_hi:[1,0,1]
	v_cvt_pk_bf16_f32 v136, v126, v127
	v_cvt_pk_bf16_f32 v138, v128, v129
	v_cvt_pk_bf16_f32 v137, v122, v123
	v_cvt_pk_bf16_f32 v139, v118, v119
	v_add_co_u32_e32 v114, vcc, 0x9038000, v110
	v_pk_fma_f32 v[120:121], v[120:121], v[150:151], v[124:125] op_sel_hi:[1,0,1]
	v_permlane16_swap_b32_e32 v136, v138
	v_permlane16_swap_b32_e32 v137, v139
	v_addc_co_u32_e32 v115, vcc, 0, v111, vcc
	global_store_dwordx4 v[114:115], v[136:139], off offset:1792
	s_and_saveexec_b64 s[22:23], s[10:11]
	s_cbranch_execz .LBB0_1281
	v_lshl_add_u64 v[124:125], s[16:17], 0, v[102:103]
	v_add_co_u32_e32 v124, vcc, 0x9040000, v124
	v_cvt_pk_bf16_f32 v114, v120, v121
	v_cvt_pk_bf16_f32 v115, v116, v117
	v_addc_co_u32_e32 v125, vcc, 0, v125, vcc
	global_store_dwordx2 v[124:125], v[114:115], off offset:1792

.LBB0_1287:
	s_cmp_lt_u32 s24, 63
	s_cselect_b64 s[22:23], -1, 0
	s_and_b64 s[30:31], s[22:23], s[8:9]
	s_and_saveexec_b64 s[24:25], s[30:31]
	s_cbranch_execz .LBB0_1289
	s_cmp_lg_u32 s29, 48
	s_cbranch_scc1 .Lch_rlx_21
	s_waitcnt vmcnt(6)
.Lch_rlx_21:
	s_waitcnt vmcnt(24)
	ds_write_b128 v131, v[10:13]
.LBB0_1289:
	s_or_b64 exec, exec, s[24:25]
	v_mov_b32_e32 v124, s28
	ds_read_b128 v[112:115], v133 offset:32256
	ds_read_b64 v[124:125], v124 offset:56
	ds_read_b128 v[136:139], v133 offset:32320
	ds_read_b128 v[144:147], v133 offset:34560
	s_andn2_b64 vcc, exec, s[22:23]
	s_cmp_lg_u32 s29, 48
	s_cbranch_scc1 .Lch_rlx_22
	s_waitcnt vmcnt(8) lgkmcnt(3)
.Lch_rlx_22:
	s_waitcnt vmcnt(22) lgkmcnt(3)
	v_mfma_f32_16x16x32_bf16 v[140:143], v[98:101], v[112:115], 0
	s_waitcnt lgkmcnt(2)
	v_add_f32_e32 v112, v134, v124
	v_max_f32_e32 v113, v125, v125
	v_max_f32_e32 v115, v112, v113
	s_cmp_lg_u32 s29, 48
	s_cbranch_scc1 .Lch_rlx_23
	s_waitcnt vmcnt(7) lgkmcnt(1)
.Lch_rlx_23:
	s_waitcnt vmcnt(21) lgkmcnt(1)
	v_mfma_f32_16x16x32_bf16 v[134:137], v[94:97], v[136:139], v[140:143]
	v_sub_f32_e32 v112, v112, v115
	v_mul_f32_e32 v112, 0x3fb8aa3b, v112
	v_exp_f32_e32 v112, v112
	ds_read_b128 v[138:141], v133 offset:34624
	s_waitcnt lgkmcnt(1)
	v_mfma_f32_16x16x32_bf16 v[142:145], v[98:101], v[144:147], 0
	v_mul_f32_e32 v113, 0xbfb8aa3b, v115
	v_exp_f32_e32 v114, v113
	v_pk_mul_f32 v[126:127], v[126:127], v[112:113] op_sel_hi:[1,0]
	v_mfma_f32_16x16x32_bf16 v[98:101], v[98:101], v[86:89], 0
	v_mul_f32_e64 v122, v122, v112
	v_mul_f32_e64 v123, v123, v112
	v_pk_fma_f32 v[126:127], v[134:135], v[114:115], v[126:127] op_sel_hi:[1,0,1]
	v_pk_fma_f32 v[124:125], v[136:137], v[114:115], v[122:123] op_sel_hi:[1,0,1]
	s_waitcnt lgkmcnt(0)
	v_mfma_f32_16x16x32_bf16 v[138:141], v[94:97], v[138:141], v[142:145]
	v_mfma_f32_16x16x32_bf16 v[94:97], v[94:97], v[86:89], v[98:101]
	s_nop 6
	v_mul_f32_e64 v122, v114, v140
	v_mul_f32_e64 v123, v114, v141
	v_pk_mul_f32 v[134:135], v[114:115], v[138:139] op_sel_hi:[0,1]
	v_pk_mul_f32 v[96:97], v[114:115], v[96:97] op_sel_hi:[0,1]
	v_pk_mul_f32 v[94:95], v[114:115], v[94:95] op_sel_hi:[0,1]
	v_pk_fma_f32 v[122:123], v[118:119], v[112:113], v[122:123] op_sel_hi:[1,0,1]
	v_pk_fma_f32 v[118:119], v[128:129], v[112:113], v[134:135] op_sel_hi:[1,0,1]
	v_pk_fma_f32 v[116:117], v[116:117], v[112:113], v[96:97] op_sel_hi:[1,0,1]
	v_pk_fma_f32 v[120:121], v[120:121], v[112:113], v[94:95] op_sel_hi:[1,0,1]
	s_cbranch_vccnz .LBB0_1214
	v_cvt_pk_bf16_f32 v94, v126, v127
	v_cvt_pk_bf16_f32 v96, v118, v119
	v_cvt_pk_bf16_f32 v95, v124, v125
	v_cvt_pk_bf16_f32 v97, v122, v123
	v_add_co_u32_e32 v98, vcc, 0x9040000, v110
	v_permlane16_swap_b32_e32 v94, v96
	v_permlane16_swap_b32_e32 v95, v97
	v_addc_co_u32_e32 v99, vcc, 0, v111, vcc
	global_store_dwordx4 v[98:99], v[94:97], off offset:2048
	s_and_saveexec_b64 s[22:23], s[10:11]
	s_cbranch_execz .LBB0_1292
	v_lshl_add_u64 v[96:97], s[16:17], 0, v[102:103]
	v_add_co_u32_e32 v96, vcc, 0x9048000, v96
	v_cvt_pk_bf16_f32 v94, v120, v121
	v_cvt_pk_bf16_f32 v95, v116, v117
	v_addc_co_u32_e32 v97, vcc, 0, v97, vcc
	global_store_dwordx2 v[96:97], v[94:95], off offset:2048
